# v17 + retention chain exact counted waits (skip paths drain) + S5 idle-lane L2 prefetch + gdn exact waits / g,beta two chunks ahead
# baseline (speedup 1.0000x reference)
.LBB0_556:
	s_waitcnt lgkmcnt(0)
	s_barrier
	ds_read_b128 v[82:85], v69 offset:27648
	ds_read_b128 v[86:89], v70 offset:46080
	ds_read_b128 v[90:93], v69 offset:36864
	ds_read_b128 v[94:97], v71 offset:46080
	ds_read_b128 v[98:101], v70 offset:27648
	ds_read_b128 v[102:105], v71 offset:27648
	s_waitcnt lgkmcnt(4)
	v_mfma_f32_16x16x32_bf16 v[86:89], v[82:85], v[86:89], 0
	v_mov_b32_e32 v29, v28
	v_pk_mul_f32 v[26:27], v[28:29], v[26:27]
	v_pk_mul_f32 v[24:25], v[42:43], v[24:25]
	s_waitcnt lgkmcnt(2)
	v_mfma_f32_16x16x32_bf16 v[82:85], v[82:85], v[94:97], 0
	ds_read_b128 v[94:97], v69 offset:27712
	v_pk_mul_f32 v[22:23], v[28:29], v[22:23]
	v_pk_mul_f32 v[20:21], v[42:43], v[20:21]
	s_waitcnt lgkmcnt(2)
	v_mfma_f32_16x16x32_bf16 v[24:27], v[90:93], v[98:101], v[24:27]
	v_add_u32_e32 v29, s2, v72
	v_lshl_or_b32 v180, v29, 10, v73
	v_add_u32_e32 v29, s2, v74
	s_waitcnt lgkmcnt(1)
	v_mfma_f32_16x16x32_bf16 v[20:23], v[90:93], v[102:105], v[20:23]
	ds_read_b128 v[90:93], v70 offset:46144
	ds_read_b128 v[98:101], v71 offset:46144
	v_or_b32_e32 v77, s0, v77
	s_mov_b32 s0, 4
	s_waitcnt lgkmcnt(1)
	v_mfma_f32_16x16x32_bf16 v[86:89], v[94:97], v[90:93], v[86:89]
	ds_read_b128 v[90:93], v69 offset:36928
	s_movk_i32 s2, 0xfff
	s_movk_i32 s4, 0x80
	s_waitcnt lgkmcnt(1)
	v_mfma_f32_16x16x32_bf16 v[82:85], v[94:97], v[98:101], v[82:85]
	ds_read_b128 v[94:97], v70 offset:27712
	ds_read_b128 v[98:101], v71 offset:27712
	s_waitcnt lgkmcnt(1)
	v_mfma_f32_16x16x32_bf16 v[24:27], v[90:93], v[94:97], v[24:27]
	ds_read_b128 v[94:97], v69 offset:64512
	ds_read_b128 v[102:105], v69 offset:64576
	ds_read_b128 v[106:109], v70 offset:18432
	s_waitcnt lgkmcnt(3)
	v_mfma_f32_16x16x32_bf16 v[20:23], v[90:93], v[98:101], v[20:23]
	ds_read_b128 v[90:93], v70 offset:18496
	ds_read_b128 v[98:101], v71 offset:18432
	ds_read_b128 v[110:113], v71 offset:18496
	s_waitcnt lgkmcnt(3)
	v_mfma_f32_16x16x32_bf16 v[86:89], v[94:97], v[106:109], v[86:89]
	v_cvt_pk_bf16_f32 v106, v24, v25
	v_cvt_pk_bf16_f32 v107, v26, v27
	ds_write_b64 v75, v[106:107] offset:55296
	s_waitcnt lgkmcnt(2)
	v_mfma_f32_16x16x32_bf16 v[82:85], v[94:97], v[98:101], v[82:85]
	v_cvt_pk_bf16_f32 v94, v20, v21
	v_cvt_pk_bf16_f32 v95, v22, v23
	ds_write_b64 v76, v[94:95] offset:55296
	v_mfma_f32_16x16x32_bf16 v[86:89], v[102:105], v[90:93], v[86:89]
	s_waitcnt lgkmcnt(2)
	v_mfma_f32_16x16x32_bf16 v[82:85], v[102:105], v[110:113], v[82:85]
	s_nop 5
	v_cvt_pk_bf16_f32 v86, v86, v87
	v_cvt_pk_bf16_f32 v87, v88, v89
	v_lshl_add_u64 v[88:89], v[180:181], 1, s[12:13]
	v_lshl_or_b32 v180, v29, 10, v73
	v_cvt_pk_bf16_f32 v82, v82, v83
	v_cvt_pk_bf16_f32 v83, v84, v85
	v_lshl_add_u64 v[84:85], v[180:181], 1, s[12:13]
	global_store_dwordx2 v[88:89], v[86:87], off offset:512
	global_store_dwordx2 v[84:85], v[82:83], off offset:512
	s_waitcnt lgkmcnt(0)
	s_barrier
	s_waitcnt vmcnt(0)
	s_branch .LBB0_558

.LBB0_558:
	s_waitcnt vmcnt(15)
	v_lshlrev_b32_e32 v82, 16, v4
	v_and_b32_e32 v83, 0xffff0000, v4
	v_lshlrev_b32_e32 v84, 16, v5
	v_and_b32_e32 v85, 0xffff0000, v5
	v_pk_mul_f32 v[82:83], v[30:31], v[82:83]
	v_pk_mul_f32 v[84:85], v[30:31], v[84:85]
	v_cvt_pk_bf16_f32 v82, v82, v83
	v_cvt_pk_bf16_f32 v83, v84, v85
	v_lshlrev_b32_e32 v84, 16, v6
	v_and_b32_e32 v85, 0xffff0000, v6
	v_lshlrev_b32_e32 v86, 16, v7
	v_and_b32_e32 v87, 0xffff0000, v7
	v_pk_mul_f32 v[84:85], v[30:31], v[84:85]
	v_pk_mul_f32 v[86:87], v[30:31], v[86:87]
	v_cvt_pk_bf16_f32 v84, v84, v85
	v_cvt_pk_bf16_f32 v85, v86, v87
	ds_write_b128 v62, v[4:7]
	s_waitcnt vmcnt(14)
	ds_write_b128 v62, v[8:11] offset:9216
	ds_write_b128 v62, v[82:85] offset:18432
	s_waitcnt vmcnt(11)
	v_lshlrev_b32_e32 v83, 16, v48
	s_waitcnt vmcnt(10)
	v_lshlrev_b32_e32 v82, 16, v50
	v_pk_mul_f32 v[82:83], v[32:33], v[82:83]
	v_lshlrev_b32_e32 v29, 16, v46
	s_mov_b32 s5, 0xffff
	v_cvt_pk_bf16_f32 v81, v82, v83
	v_lshrrev_b32_e32 v82, 16, v44
	v_and_or_b32 v29, v44, s5, v29
	v_and_or_b32 v82, v46, s60, v82
	ds_write2_b32 v63, v29, v82 offset1:36
	v_and_b32_e32 v83, 0xffff0000, v48
	v_and_b32_e32 v82, 0xffff0000, v50
	v_pk_mul_f32 v[82:83], v[32:33], v[82:83]
	s_cmpk_lt_u32 s0, 0x42
	v_cvt_pk_bf16_f32 v29, v82, v83
	v_lshlrev_b32_e32 v83, 16, v49
	v_lshlrev_b32_e32 v82, 16, v51
	v_pk_mul_f32 v[82:83], v[32:33], v[82:83]
	ds_write2_b32 v64, v81, v29 offset1:36
	v_lshlrev_b32_e32 v29, 16, v47
	v_cvt_pk_bf16_f32 v81, v82, v83
	v_lshrrev_b32_e32 v82, 16, v45
	v_and_or_b32 v29, v45, s5, v29
	v_and_or_b32 v82, v47, s60, v82
	ds_write2_b32 v63, v29, v82 offset0:72 offset1:108
	v_and_b32_e32 v83, 0xffff0000, v49
	v_and_b32_e32 v82, 0xffff0000, v51
	s_cselect_b64 s[16:17], -1, 0
	s_cmpk_gt_u32 s0, 0x41
	v_pk_mul_f32 v[82:83], v[32:33], v[82:83]
	s_cselect_b64 s[14:15], -1, 0
	v_cvt_pk_bf16_f32 v29, v82, v83
	s_and_b64 vcc, exec, s[14:15]
	ds_write2_b32 v64, v81, v29 offset0:72 offset1:108
	s_waitcnt lgkmcnt(0)
	s_barrier
	s_cbranch_vccnz .Lret_skipA
	s_add_i32 s5, s2, 0xffffff80
	s_and_b64 s[18:19], s[8:9], exec
	s_cselect_b32 s5, s4, s5
	s_add_i32 s5, s5, s1
	v_add_u32_e32 v4, s5, v60
	v_add_u32_e32 v29, s5, v67
	v_mul_u32_u24_e32 v4, 0xe00, v4
	v_mad_u32_u24 v44, v29, s63, v61
	v_or_b32_e32 v4, v4, v77
	v_ashrrev_i32_e32 v45, 31, v44
	v_ashrrev_i32_e32 v5, 31, v4
	v_lshl_add_u64 v[50:51], v[44:45], 1, s[82:83]
	v_lshl_add_u64 v[8:9], v[4:5], 1, s[82:83]
	v_lshl_add_u64 v[48:49], s[10:11], 1, v[50:51]
	global_load_dwordx4 v[4:7], v[8:9], off offset:2560
	s_nop 0
	global_load_dwordx4 v[8:11], v[8:9], off offset:3072
	s_nop 0
	global_load_dwordx2 v[44:45], v[50:51], off offset:3584
	global_load_dwordx2 v[46:47], v[48:49], off offset:3584
	s_nop 0
	global_load_dwordx2 v[48:49], v[48:49], off offset:3072
	s_nop 0
	global_load_dwordx2 v[50:51], v[50:51], off offset:3072

.LBB0_562:
	s_waitcnt lgkmcnt(0)
	s_barrier
	ds_read_b128 v[82:85], v69 offset:27648
	ds_read_b128 v[86:89], v70 offset:46080
	ds_read_b128 v[90:93], v69 offset:36864
	ds_read_b128 v[94:97], v71 offset:46080
	ds_read_b128 v[98:101], v70 offset:27648
	ds_read_b128 v[102:105], v71 offset:27648
	s_waitcnt lgkmcnt(4)
	v_mfma_f32_16x16x32_bf16 v[86:89], v[82:85], v[86:89], 0
	v_mov_b32_e32 v29, v28
	v_pk_mul_f32 v[26:27], v[28:29], v[26:27]
	v_pk_mul_f32 v[24:25], v[42:43], v[24:25]
	s_waitcnt lgkmcnt(2)
	v_mfma_f32_16x16x32_bf16 v[82:85], v[82:85], v[94:97], 0
	ds_read_b128 v[94:97], v69 offset:27712
	v_pk_mul_f32 v[22:23], v[28:29], v[22:23]
	v_pk_mul_f32 v[20:21], v[42:43], v[20:21]
	s_waitcnt lgkmcnt(2)
	v_mfma_f32_16x16x32_bf16 v[24:27], v[90:93], v[98:101], v[24:27]
	s_add_i32 s5, s4, 0xffffff80
	s_and_b64 s[18:19], s[8:9], exec
	s_cselect_b32 s5, s5, s2
	s_waitcnt lgkmcnt(1)
	v_mfma_f32_16x16x32_bf16 v[20:23], v[90:93], v[102:105], v[20:23]
	ds_read_b128 v[90:93], v70 offset:46144
	ds_read_b128 v[98:101], v71 offset:46144
	s_add_i32 s5, s5, s1
	v_add_u32_e32 v29, s5, v72
	s_waitcnt lgkmcnt(1)
	v_mfma_f32_16x16x32_bf16 v[86:89], v[94:97], v[90:93], v[86:89]
	ds_read_b128 v[90:93], v69 offset:36928
	v_lshl_or_b32 v180, v29, 10, v73
	v_add_u32_e32 v29, s5, v74
	s_waitcnt lgkmcnt(1)
	v_mfma_f32_16x16x32_bf16 v[82:85], v[94:97], v[98:101], v[82:85]
	ds_read_b128 v[94:97], v70 offset:27712
	ds_read_b128 v[98:101], v71 offset:27712
	ds_read_b128 v[102:105], v70 offset:18432
	s_mov_b32 s5, 0xffff
	s_waitcnt lgkmcnt(2)
	v_mfma_f32_16x16x32_bf16 v[24:27], v[90:93], v[94:97], v[24:27]
	ds_read_b128 v[94:97], v69 offset:55296
	s_andn2_b64 vcc, exec, s[16:17]
	s_waitcnt lgkmcnt(2)
	v_mfma_f32_16x16x32_bf16 v[20:23], v[90:93], v[98:101], v[20:23]
	ds_read_b128 v[90:93], v69 offset:55360
	ds_read_b128 v[98:101], v70 offset:18496
	ds_read_b128 v[106:109], v71 offset:18432
	s_waitcnt lgkmcnt(3)
	v_mfma_f32_16x16x32_bf16 v[86:89], v[94:97], v[102:105], v[86:89]
	ds_read_b128 v[102:105], v71 offset:18496
	s_waitcnt lgkmcnt(1)
	v_mfma_f32_16x16x32_bf16 v[82:85], v[94:97], v[106:109], v[82:85]
	v_cvt_pk_bf16_f32 v94, v24, v25
	v_cvt_pk_bf16_f32 v95, v26, v27
	ds_write_b64 v75, v[94:95] offset:64512
	v_mfma_f32_16x16x32_bf16 v[86:89], v[90:93], v[98:101], v[86:89]
	v_cvt_pk_bf16_f32 v94, v20, v21
	v_cvt_pk_bf16_f32 v95, v22, v23
	ds_write_b64 v76, v[94:95] offset:64512
	s_waitcnt lgkmcnt(2)
	v_mfma_f32_16x16x32_bf16 v[82:85], v[90:93], v[102:105], v[82:85]
	s_nop 2
	v_cvt_pk_bf16_f32 v86, v86, v87
	v_cvt_pk_bf16_f32 v87, v88, v89
	v_lshl_add_u64 v[88:89], v[180:181], 1, s[12:13]
	v_lshl_or_b32 v180, v29, 10, v73
	s_nop 0
	v_cvt_pk_bf16_f32 v82, v82, v83
	v_cvt_pk_bf16_f32 v83, v84, v85
	v_lshl_add_u64 v[84:85], v[180:181], 1, s[12:13]
	global_store_dwordx2 v[88:89], v[86:87], off offset:512
	global_store_dwordx2 v[84:85], v[82:83], off offset:512
	s_waitcnt vmcnt(15)
	v_lshlrev_b32_e32 v82, 16, v12
	v_and_b32_e32 v83, 0xffff0000, v12
	v_lshlrev_b32_e32 v84, 16, v13
	v_and_b32_e32 v85, 0xffff0000, v13
	v_pk_mul_f32 v[82:83], v[30:31], v[82:83]
	v_pk_mul_f32 v[84:85], v[30:31], v[84:85]
	v_cvt_pk_bf16_f32 v82, v82, v83
	v_cvt_pk_bf16_f32 v83, v84, v85
	v_lshlrev_b32_e32 v84, 16, v14
	v_and_b32_e32 v85, 0xffff0000, v14
	v_lshlrev_b32_e32 v86, 16, v15
	v_and_b32_e32 v87, 0xffff0000, v15
	v_pk_mul_f32 v[84:85], v[30:31], v[84:85]
	v_pk_mul_f32 v[86:87], v[30:31], v[86:87]
	v_cvt_pk_bf16_f32 v84, v84, v85
	v_cvt_pk_bf16_f32 v85, v86, v87
	s_waitcnt lgkmcnt(0)
	s_barrier
	ds_write_b128 v62, v[12:15]
	s_waitcnt vmcnt(14)
	ds_write_b128 v62, v[16:19] offset:9216
	ds_write_b128 v62, v[82:85] offset:18432
	s_waitcnt vmcnt(11)
	v_lshlrev_b32_e32 v83, 16, v56
	s_waitcnt vmcnt(10)
	v_lshlrev_b32_e32 v82, 16, v58
	v_pk_mul_f32 v[82:83], v[32:33], v[82:83]
	v_lshlrev_b32_e32 v29, 16, v54
	v_cvt_pk_bf16_f32 v81, v82, v83
	v_lshrrev_b32_e32 v82, 16, v52
	v_and_or_b32 v29, v52, s5, v29
	v_and_or_b32 v82, v54, s60, v82
	ds_write2_b32 v63, v29, v82 offset1:36
	v_and_b32_e32 v83, 0xffff0000, v56
	v_and_b32_e32 v82, 0xffff0000, v58
	v_pk_mul_f32 v[82:83], v[32:33], v[82:83]
	s_nop 0
	v_cvt_pk_bf16_f32 v29, v82, v83
	v_lshlrev_b32_e32 v83, 16, v57
	v_lshlrev_b32_e32 v82, 16, v59
	v_pk_mul_f32 v[82:83], v[32:33], v[82:83]
	ds_write2_b32 v64, v81, v29 offset1:36
	v_lshlrev_b32_e32 v29, 16, v55
	v_cvt_pk_bf16_f32 v81, v82, v83
	v_lshrrev_b32_e32 v82, 16, v53
	v_and_or_b32 v29, v53, s5, v29
	v_and_or_b32 v82, v55, s60, v82
	ds_write2_b32 v63, v29, v82 offset0:72 offset1:108
	v_and_b32_e32 v83, 0xffff0000, v57
	v_and_b32_e32 v82, 0xffff0000, v59
	v_pk_mul_f32 v[82:83], v[32:33], v[82:83]
	s_nop 0
	v_cvt_pk_bf16_f32 v29, v82, v83
	ds_write2_b32 v64, v81, v29 offset0:72 offset1:108
	s_waitcnt lgkmcnt(0)
	s_barrier
	s_cbranch_vccnz .Lret_skipB
	s_add_i32 s5, s4, 64
	s_add_i32 s18, s2, 0xffffff40
	s_and_b64 s[16:17], s[8:9], exec
	s_cselect_b32 s5, s5, s18
	s_add_i32 s5, s5, s1
	v_add_u32_e32 v12, s5, v60
	v_add_u32_e32 v29, s5, v67
	v_mul_u32_u24_e32 v12, 0xe00, v12
	v_mad_u32_u24 v52, v29, s63, v61
	v_or_b32_e32 v12, v12, v77
	v_ashrrev_i32_e32 v53, 31, v52
	v_ashrrev_i32_e32 v13, 31, v12
	v_lshl_add_u64 v[58:59], v[52:53], 1, s[82:83]
	v_lshl_add_u64 v[16:17], v[12:13], 1, s[82:83]
	v_lshl_add_u64 v[56:57], s[10:11], 1, v[58:59]
	global_load_dwordx4 v[12:15], v[16:17], off offset:2560
	s_nop 0
	global_load_dwordx4 v[16:19], v[16:17], off offset:3072
	s_nop 0
	global_load_dwordx2 v[52:53], v[58:59], off offset:3584
	global_load_dwordx2 v[54:55], v[56:57], off offset:3584
	s_nop 0
	global_load_dwordx2 v[56:57], v[56:57], off offset:3072
	s_nop 0
	global_load_dwordx2 v[58:59], v[58:59], off offset:3072
.LBB0_564:
	ds_read_b128 v[82:85], v65 offset:9216
	ds_read_b128 v[86:89], v66
	ds_read_b128 v[90:93], v65 offset:9280
	s_and_b64 vcc, exec, s[6:7]
	s_waitcnt lgkmcnt(1)
	v_mfma_f32_16x16x32_bf16 v[82:85], v[82:85], v[86:89], 0
	ds_read_b128 v[86:89], v66 offset:64
	s_waitcnt lgkmcnt(0)
	v_mfma_f32_16x16x32_bf16 v[82:85], v[90:93], v[86:89], v[82:85]
	s_nop 7
	v_pk_mul_f32 v[82:83], v[34:35], v[82:83]
	v_pk_mul_f32 v[84:85], v[38:39], v[84:85]
	v_cvt_pk_bf16_f32 v82, v82, v83
	v_cvt_pk_bf16_f32 v83, v84, v85
	ds_write_b64 v68, v[82:83] offset:46080
	s_cbranch_vccnz .LBB0_557
	ds_read_b128 v[82:85], v78 offset:9216
	ds_read_b128 v[86:89], v79
	ds_read_b128 v[90:93], v78 offset:9280
	s_waitcnt lgkmcnt(1)
	v_mfma_f32_16x16x32_bf16 v[82:85], v[82:85], v[86:89], 0
	ds_read_b128 v[86:89], v79 offset:64
	s_waitcnt lgkmcnt(0)
	v_mfma_f32_16x16x32_bf16 v[82:85], v[90:93], v[86:89], v[82:85]
	s_nop 7
	v_pk_mul_f32 v[82:83], v[36:37], v[82:83]
	v_pk_mul_f32 v[84:85], v[40:41], v[84:85]
	v_cvt_pk_bf16_f32 v82, v82, v83
	v_cvt_pk_bf16_f32 v83, v84, v85
	ds_write_b64 v80, v[82:83] offset:46080
	s_branch .LBB0_557
.Lret_skipA:
	s_waitcnt vmcnt(0)
	s_branch .LBB0_560
.Lret_skipB:
	s_waitcnt vmcnt(0)
	s_branch .LBB0_564
.LBB0_566:
	v_readlane_b32 s66, v255, 18
	v_readlane_b32 s68, v255, 20
	s_mov_b64 s[4:5], 0
	v_readlane_b32 s62, v255, 27
	v_readlane_b32 s67, v255, 19
	v_readlane_b32 s69, v255, 21
	v_readlane_b32 s63, v255, 26
	s_mov_b32 s65, 0x1930000
	s_mov_b32 s70, 0x8000
	s_mov_b32 s71, 0x1c000
	s_mov_b32 s73, 0xe000
	s_movk_i32 s72, 0x1ff
	s_movk_i32 s74, 0x200
	s_mov_b32 s77, 0x28c1979
	s_movk_i32 s87, 0x33f
	s_movk_i32 s76, 0x37f
	s_movk_i32 s86, 0x800
	s_movk_i32 s83, 0x1000
	s_movk_i32 s84, 0x3000
	s_mov_b32 s85, 0x38000
	s_mov_b32 s82, 0x70000
